# P3 hgrn_scan loads hoisted (8 steps per round trip) on top of P9 hand-written loop+tile and head-major QKV layout
# baseline (speedup 1.0000x reference)
; #define GAS __attribute__((address_space(1)))
; __device__ __forceinline__ unsigned pk2(float lo, float hi) { f32x2 v = {lo, hi}; bf16x2_t b = __builtin_convertvector(v, bf16x2_t); return __builtin_bit_cast(unsigned, b); }
; __device__ __forceinline__ void hgrn_scan(Frame& F) {
;     const float* SL = WSP(float, WS_SL); const float* DT = WSP(float, WS_DT); bf16* SS = WSP(bf16, WS_SS); float* SHP = F.out + O_SHP;
;     for (int idx = F.bid * 512 + F.tid; idx < 32 * 128 * 32; idx += F.G * 512) {
;         const int bh = idx >> 12, v = (idx >> 5) & 127, k = (idx & 31) * 4;
;         f32x4 s = (f32x4){0.f, 0.f, 0.f, 0.f};
; #pragma unroll 4
;         for (int j = 0; j < 16; ++j) { const int it = bh * 16 + j;
;             *(GAS v2u*)(SS + (size_t)it * 16384 + v * 128 + k) = (v2u){pk2(s.x, s.y), pk2(s.z, s.w)};
;             const f32x4 d = *(const GAS f32x4*)(DT + it * 128 + k), sl = *(const GAS f32x4*)(SL + (size_t)it * 16384 + v * 128 + k);
;             s = d * s + sl; }
; #pragma unroll
;         for (int e = 0; e < 4; ++e) SHP[(size_t)bh * 16384 + (k + e) * 128 + v] = s[e];
;     }
; }
.LBB0_745:
	v_lshlrev_b32_e32 v4, 4, v16
	v_and_b32_e32 v12, 0xfe00, v4
	v_lshlrev_b32_e32 v4, 3, v16
	v_and_b32_e32 v13, 0x7f00, v4
	v_lshlrev_b32_e32 v4, 1, v17
	v_and_b32_e32 v14, 0xf8, v4
	v_ashrrev_i32_e32 v4, 12, v16
	v_lshlrev_b32_e32 v10, 4, v4
	v_lshlrev_b32_e32 v6, 11, v4
	v_lshlrev_b32_e32 v2, 2, v17
	v_ashrrev_i32_e32 v7, 31, v6
	v_ashrrev_i32_e32 v11, 31, v10
	v_and_b32_e32 v5, 0x1f0, v2
	v_lshlrev_b64 v[6:7], 2, v[6:7]
	v_lshlrev_b64 v[8:9], 16, v[10:11]
	v_lshlrev_b64 v[10:11], 15, v[10:11]
	v_lshrrev_b32_e32 v2, 5, v16
	v_or_b32_e32 v6, v6, v5
	v_or3_b32 v8, v8, v12, v5
	v_or3_b32 v10, v10, v13, v14
	s_mov_b32 s34, 16
	v_mov_b32_e32 v14, 0
	v_mov_b32_e32 v15, v3
	v_mov_b32_e32 v12, 0
	v_mov_b32_e32 v13, v3
	s_waitcnt vmcnt(0)
	s_mov_b64 s[98:99], 0x10000
	s_mov_b64 s[100:101], 0x8000
	s_mov_b32 s34, 0x18a00000
	s_mov_b32 s35, 0
	v_lshl_add_u64 v[26:27], s[30:31], 0, v[6:7]
	v_lshl_add_u64 v[26:27], v[26:27], 0, s[34:35]
	s_mov_b32 s34, 0x16a00000
	v_lshl_add_u64 v[28:29], s[30:31], 0, v[8:9]
	v_lshl_add_u64 v[28:29], v[28:29], 0, s[34:35]
	s_mov_b32 s34, 0x18b00000
	v_lshl_add_u64 v[30:31], s[30:31], 0, v[10:11]
	v_lshl_add_u64 v[30:31], v[30:31], 0, s[34:35]
	s_mov_b64 s[34:35], 0x1000
	global_load_dwordx4 v[180:183], v[26:27], off
	global_load_dwordx4 v[184:187], v[26:27], off offset:512
	global_load_dwordx4 v[188:191], v[26:27], off offset:1024
	global_load_dwordx4 v[192:195], v[26:27], off offset:1536
	global_load_dwordx4 v[196:199], v[26:27], off offset:2048
	global_load_dwordx4 v[200:203], v[26:27], off offset:2560
	global_load_dwordx4 v[204:207], v[26:27], off offset:3072
	global_load_dwordx4 v[208:211], v[26:27], off offset:3584
	v_lshl_add_u64 v[26:27], v[26:27], 0, s[34:35]
	global_load_dwordx4 v[212:215], v[28:29], off
	v_lshl_add_u64 v[28:29], v[28:29], 0, s[98:99]
	global_load_dwordx4 v[216:219], v[28:29], off
	v_lshl_add_u64 v[28:29], v[28:29], 0, s[98:99]
	global_load_dwordx4 v[220:223], v[28:29], off
	v_lshl_add_u64 v[28:29], v[28:29], 0, s[98:99]
	global_load_dwordx4 v[224:227], v[28:29], off
	v_lshl_add_u64 v[28:29], v[28:29], 0, s[98:99]
	global_load_dwordx4 v[228:231], v[28:29], off
	v_lshl_add_u64 v[28:29], v[28:29], 0, s[98:99]
	global_load_dwordx4 v[232:235], v[28:29], off
	v_lshl_add_u64 v[28:29], v[28:29], 0, s[98:99]
	global_load_dwordx4 v[236:239], v[28:29], off
	v_lshl_add_u64 v[28:29], v[28:29], 0, s[98:99]
	global_load_dwordx4 v[240:243], v[28:29], off
	v_lshl_add_u64 v[28:29], v[28:29], 0, s[98:99]
	s_waitcnt vmcnt(7)
	v_cvt_pk_bf16_f32 v18, v14, v15
	v_cvt_pk_bf16_f32 v19, v12, v13
	global_store_dwordx2 v[30:31], v[18:19], off
	v_lshl_add_u64 v[30:31], v[30:31], 0, s[100:101]
	v_pk_fma_f32 v[14:15], v[14:15], v[180:181], v[212:213]
	v_pk_fma_f32 v[12:13], v[12:13], v[182:183], v[214:215]
	s_waitcnt vmcnt(7)
	v_cvt_pk_bf16_f32 v18, v14, v15
	v_cvt_pk_bf16_f32 v19, v12, v13
	global_store_dwordx2 v[30:31], v[18:19], off
	v_lshl_add_u64 v[30:31], v[30:31], 0, s[100:101]
	v_pk_fma_f32 v[14:15], v[14:15], v[184:185], v[216:217]
	v_pk_fma_f32 v[12:13], v[12:13], v[186:187], v[218:219]
	s_waitcnt vmcnt(7)
	v_cvt_pk_bf16_f32 v18, v14, v15
	v_cvt_pk_bf16_f32 v19, v12, v13
	global_store_dwordx2 v[30:31], v[18:19], off
	v_lshl_add_u64 v[30:31], v[30:31], 0, s[100:101]
	v_pk_fma_f32 v[14:15], v[14:15], v[188:189], v[220:221]
	v_pk_fma_f32 v[12:13], v[12:13], v[190:191], v[222:223]
	s_waitcnt vmcnt(7)
	v_cvt_pk_bf16_f32 v18, v14, v15
	v_cvt_pk_bf16_f32 v19, v12, v13
	global_store_dwordx2 v[30:31], v[18:19], off
	v_lshl_add_u64 v[30:31], v[30:31], 0, s[100:101]
	v_pk_fma_f32 v[14:15], v[14:15], v[192:193], v[224:225]
	v_pk_fma_f32 v[12:13], v[12:13], v[194:195], v[226:227]
	s_waitcnt vmcnt(7)
	v_cvt_pk_bf16_f32 v18, v14, v15
	v_cvt_pk_bf16_f32 v19, v12, v13
	global_store_dwordx2 v[30:31], v[18:19], off
	v_lshl_add_u64 v[30:31], v[30:31], 0, s[100:101]
	v_pk_fma_f32 v[14:15], v[14:15], v[196:197], v[228:229]
	v_pk_fma_f32 v[12:13], v[12:13], v[198:199], v[230:231]
	s_waitcnt vmcnt(7)
	v_cvt_pk_bf16_f32 v18, v14, v15
	v_cvt_pk_bf16_f32 v19, v12, v13
	global_store_dwordx2 v[30:31], v[18:19], off
	v_lshl_add_u64 v[30:31], v[30:31], 0, s[100:101]
	v_pk_fma_f32 v[14:15], v[14:15], v[200:201], v[232:233]
	v_pk_fma_f32 v[12:13], v[12:13], v[202:203], v[234:235]
	s_waitcnt vmcnt(7)
	v_cvt_pk_bf16_f32 v18, v14, v15
	v_cvt_pk_bf16_f32 v19, v12, v13
	global_store_dwordx2 v[30:31], v[18:19], off
	v_lshl_add_u64 v[30:31], v[30:31], 0, s[100:101]
	v_pk_fma_f32 v[14:15], v[14:15], v[204:205], v[236:237]
	v_pk_fma_f32 v[12:13], v[12:13], v[206:207], v[238:239]
	s_waitcnt vmcnt(7)
; #define GAS __attribute__((address_space(1)))
; __device__ __forceinline__ unsigned pk2(float lo, float hi) { f32x2 v = {lo, hi}; bf16x2_t b = __builtin_convertvector(v, bf16x2_t); return __builtin_bit_cast(unsigned, b); }
; __device__ __forceinline__ void hgrn_scan(Frame& F) {
;     const float* SL = WSP(float, WS_SL); const float* DT = WSP(float, WS_DT); bf16* SS = WSP(bf16, WS_SS); float* SHP = F.out + O_SHP;
;     for (int idx = F.bid * 512 + F.tid; idx < 32 * 128 * 32; idx += F.G * 512) {
;         const int bh = idx >> 12, v = (idx >> 5) & 127, k = (idx & 31) * 4;
;         f32x4 s = (f32x4){0.f, 0.f, 0.f, 0.f};
; #pragma unroll 4
;         for (int j = 0; j < 16; ++j) { const int it = bh * 16 + j;
;             *(GAS v2u*)(SS + (size_t)it * 16384 + v * 128 + k) = (v2u){pk2(s.x, s.y), pk2(s.z, s.w)};
;             const f32x4 d = *(const GAS f32x4*)(DT + it * 128 + k), sl = *(const GAS f32x4*)(SL + (size_t)it * 16384 + v * 128 + k);
;             s = d * s + sl; }
; #pragma unroll
;         for (int e = 0; e < 4; ++e) SHP[(size_t)bh * 16384 + (k + e) * 128 + v] = s[e];
;     }
; }
	v_cvt_pk_bf16_f32 v18, v14, v15
	v_cvt_pk_bf16_f32 v19, v12, v13
	global_store_dwordx2 v[30:31], v[18:19], off
	v_lshl_add_u64 v[30:31], v[30:31], 0, s[100:101]
	v_pk_fma_f32 v[14:15], v[14:15], v[208:209], v[240:241]
	v_pk_fma_f32 v[12:13], v[12:13], v[210:211], v[242:243]
	s_nop 1
	global_load_dwordx4 v[180:183], v[26:27], off
	global_load_dwordx4 v[184:187], v[26:27], off offset:512
	global_load_dwordx4 v[188:191], v[26:27], off offset:1024
	global_load_dwordx4 v[192:195], v[26:27], off offset:1536
	global_load_dwordx4 v[196:199], v[26:27], off offset:2048
	global_load_dwordx4 v[200:203], v[26:27], off offset:2560
	global_load_dwordx4 v[204:207], v[26:27], off offset:3072
	global_load_dwordx4 v[208:211], v[26:27], off offset:3584
	v_lshl_add_u64 v[26:27], v[26:27], 0, s[34:35]
	global_load_dwordx4 v[212:215], v[28:29], off
	v_lshl_add_u64 v[28:29], v[28:29], 0, s[98:99]
	global_load_dwordx4 v[216:219], v[28:29], off
	v_lshl_add_u64 v[28:29], v[28:29], 0, s[98:99]
	global_load_dwordx4 v[220:223], v[28:29], off
	v_lshl_add_u64 v[28:29], v[28:29], 0, s[98:99]
	global_load_dwordx4 v[224:227], v[28:29], off
	v_lshl_add_u64 v[28:29], v[28:29], 0, s[98:99]
	global_load_dwordx4 v[228:231], v[28:29], off
	v_lshl_add_u64 v[28:29], v[28:29], 0, s[98:99]
	global_load_dwordx4 v[232:235], v[28:29], off
	v_lshl_add_u64 v[28:29], v[28:29], 0, s[98:99]
	global_load_dwordx4 v[236:239], v[28:29], off
	v_lshl_add_u64 v[28:29], v[28:29], 0, s[98:99]
	global_load_dwordx4 v[240:243], v[28:29], off
	v_lshl_add_u64 v[28:29], v[28:29], 0, s[98:99]
	s_waitcnt vmcnt(7)
	v_cvt_pk_bf16_f32 v18, v14, v15
	v_cvt_pk_bf16_f32 v19, v12, v13
	global_store_dwordx2 v[30:31], v[18:19], off
	v_lshl_add_u64 v[30:31], v[30:31], 0, s[100:101]
	v_pk_fma_f32 v[14:15], v[14:15], v[180:181], v[212:213]
	v_pk_fma_f32 v[12:13], v[12:13], v[182:183], v[214:215]
	s_waitcnt vmcnt(7)
	v_cvt_pk_bf16_f32 v18, v14, v15
	v_cvt_pk_bf16_f32 v19, v12, v13
	global_store_dwordx2 v[30:31], v[18:19], off
	v_lshl_add_u64 v[30:31], v[30:31], 0, s[100:101]
	v_pk_fma_f32 v[14:15], v[14:15], v[184:185], v[216:217]
	v_pk_fma_f32 v[12:13], v[12:13], v[186:187], v[218:219]
	s_waitcnt vmcnt(7)
	v_cvt_pk_bf16_f32 v18, v14, v15
	v_cvt_pk_bf16_f32 v19, v12, v13
	global_store_dwordx2 v[30:31], v[18:19], off
	v_lshl_add_u64 v[30:31], v[30:31], 0, s[100:101]
	v_pk_fma_f32 v[14:15], v[14:15], v[188:189], v[220:221]
	v_pk_fma_f32 v[12:13], v[12:13], v[190:191], v[222:223]
	s_waitcnt vmcnt(7)
	v_cvt_pk_bf16_f32 v18, v14, v15
	v_cvt_pk_bf16_f32 v19, v12, v13
	global_store_dwordx2 v[30:31], v[18:19], off
	v_lshl_add_u64 v[30:31], v[30:31], 0, s[100:101]
	v_pk_fma_f32 v[14:15], v[14:15], v[192:193], v[224:225]
	v_pk_fma_f32 v[12:13], v[12:13], v[194:195], v[226:227]
	s_waitcnt vmcnt(7)
	v_cvt_pk_bf16_f32 v18, v14, v15
	v_cvt_pk_bf16_f32 v19, v12, v13
	global_store_dwordx2 v[30:31], v[18:19], off
	v_lshl_add_u64 v[30:31], v[30:31], 0, s[100:101]
	v_pk_fma_f32 v[14:15], v[14:15], v[196:197], v[228:229]
	v_pk_fma_f32 v[12:13], v[12:13], v[198:199], v[230:231]
	s_waitcnt vmcnt(7)
	v_cvt_pk_bf16_f32 v18, v14, v15
	v_cvt_pk_bf16_f32 v19, v12, v13
	global_store_dwordx2 v[30:31], v[18:19], off
	v_lshl_add_u64 v[30:31], v[30:31], 0, s[100:101]
	v_pk_fma_f32 v[14:15], v[14:15], v[200:201], v[232:233]
	v_pk_fma_f32 v[12:13], v[12:13], v[202:203], v[234:235]
	s_waitcnt vmcnt(7)
	v_cvt_pk_bf16_f32 v18, v14, v15
	v_cvt_pk_bf16_f32 v19, v12, v13
	global_store_dwordx2 v[30:31], v[18:19], off
	v_lshl_add_u64 v[30:31], v[30:31], 0, s[100:101]
	v_pk_fma_f32 v[14:15], v[14:15], v[204:205], v[236:237]
	v_pk_fma_f32 v[12:13], v[12:13], v[206:207], v[238:239]
	s_waitcnt vmcnt(7)
	v_cvt_pk_bf16_f32 v18, v14, v15
	v_cvt_pk_bf16_f32 v19, v12, v13
	global_store_dwordx2 v[30:31], v[18:19], off
	v_lshl_add_u64 v[30:31], v[30:31], 0, s[100:101]
	v_pk_fma_f32 v[14:15], v[14:15], v[208:209], v[240:241]
	v_pk_fma_f32 v[12:13], v[12:13], v[210:211], v[242:243]
	v_ashrrev_i32_e32 v5, 31, v4
	v_and_b32_e32 v2, 0x7f, v2
	v_lshlrev_b64 v[4:5], 16, v[4:5]
	v_lshl_add_u64 v[4:5], s[6:7], 0, v[4:5]
	v_lshlrev_b32_e32 v2, 2, v2
	v_lshl_add_u64 v[4:5], v[4:5], 0, v[2:3]
	v_lshlrev_b32_e32 v2, 11, v16
	v_add_u32_e32 v16, s0, v16
	v_and_b32_e32 v2, 0xf800, v2
	v_cmp_lt_i32_e32 vcc, s33, v16
	v_lshl_add_u64 v[4:5], v[4:5], 0, v[2:3]
	s_or_b64 s[8:9], vcc, s[8:9]
	v_add_u32_e32 v17, s1, v17
	global_store_dword v[4:5], v14, off
	global_store_dword v[4:5], v15, off offset:512
	global_store_dword v[4:5], v12, off offset:1024
	global_store_dword v[4:5], v13, off offset:1536
	s_andn2_b64 exec, exec, s[8:9]
	s_cbranch_execnz .LBB0_745

.Lp9n_loop:
.Lp9n_stepA:
	s_add_i32 s23, s20, 3
	v_readlane_b32 s22, v104, s20
	v_readlane_b32 s23, v104, s23
	s_mul_i32 s24, s21, 0x4800
	s_waitcnt vmcnt(27)
	v_add_u32_e32 v109, s24, v100
	ds_write_b128 v109, v[26:29]
	ds_write_b128 v109, v[30:33] offset:55296
	ds_write_b128 v109, v[34:37] offset:9216
	ds_write_b128 v109, v[38:41] offset:64512
	v_mov_b64_e32 v[18:19], v[2:3]
	v_mov_b64_e32 v[20:21], v[4:5]
	v_mov_b64_e32 v[22:23], v[6:7]
	v_mov_b64_e32 v[24:25], v[8:9]
	s_waitcnt lgkmcnt(0)
	s_barrier
	s_bfe_u32 s36, s23, 0x20000
	s_bfe_u32 s37, s23, 0x40002
	s_bfe_u32 s38, s23, 0x60006
	s_bfe_u32 s39, s23, 0x8000c
	s_lshl_b32 s40, s36, 1
	s_lshr_b32 s40, 0x1000, s40
	s_mul_i32 s39, s39, s40
	s_add_i32 s38, s38, -1
	s_lshl_b32 s38, s38, 7
	s_add_i32 s39, s39, s38
	s_lshl_b32 s39, s39, 7
	s_mul_i32 s37, s37, 0x208000
	s_add_i32 s39, s39, s37
	s_bitcmp1_b32 s23, 21
	s_cselect_b32 s39, s39, 0x80000000
	s_mul_i32 s36, s36, 0x2100000
	s_add_i32 s40, s36, 0x16a00000
	s_add_i32 s41, s36, 0x1cd00000
	s_add_i32 s42, s36, 0x10700000
	v_add_u32_e32 v105, s39, v101
	v_add_u32_e32 v106, s39, v102
	v_add_u32_e32 v107, s39, v103
	s_bitcmp1_b32 s22, 20
	s_cbranch_scc0 .Lp9n_nocompA
	s_and_b32 s99, s22, 63
	s_bfe_u32 s4, s22, 0x60006
	s_add_i32 s4, s4, -1
	s_lshl_b32 s4, s4, 6
	s_or_b32 s99, s99, s4
	s_add_i32 s4, s21, -1
	s_cmp_lt_i32 s4, 0
	s_cselect_b32 s4, 2, s4
	s_lshl_b32 s4, s4, 3
	s_lshr_b32 s5, s33, 4
	s_add_i32 s4, s4, s5
	s_lshl_b32 s4, s4, 11
	s_or_b32 s99, s99, s4
	s_bfe_u32 s4, s22, 0x8000c
	s_lshl_b32 s4, s4, 17
	s_or_b32 s99, s99, s4
	buffer_load_dwordx4 v[26:29], v105, s[16:19], s40 offen
	buffer_load_dwordx4 v[30:33], v105, s[16:19], s41 offen
	buffer_load_dwordx4 v[34:37], v106, s[16:19], s40 offen
	buffer_load_dwordx4 v[38:41], v106, s[16:19], s41 offen
	buffer_load_dwordx4 v[2:5], v107, s[16:19], s42 offen
	buffer_load_dwordx4 v[6:9], v107, s[16:19], s42 offen offset:64
	s_bitset1_b32 s99, 26
	s_branch .Lat_tile
.Lp9n_nocompA:
	buffer_load_dwordx4 v[26:29], v105, s[16:19], s40 offen
	buffer_load_dwordx4 v[30:33], v105, s[16:19], s41 offen
	buffer_load_dwordx4 v[34:37], v106, s[16:19], s40 offen
	buffer_load_dwordx4 v[38:41], v106, s[16:19], s41 offen
	buffer_load_dwordx4 v[2:5], v107, s[16:19], s42 offen
	buffer_load_dwordx4 v[6:9], v107, s[16:19], s42 offen offset:64
	buffer_store_dword v108, v108, s[16:19], 0 offen
	buffer_store_dword v108, v108, s[16:19], 0 offen
	buffer_store_dword v108, v108, s[16:19], 0 offen
	buffer_store_dword v108, v108, s[16:19], 0 offen
	buffer_store_dword v108, v108, s[16:19], 0 offen

.Lp9n_stepB:
	s_add_i32 s23, s20, 3
	v_readlane_b32 s22, v104, s20
	v_readlane_b32 s23, v104, s23
	s_mul_i32 s24, s21, 0x4800
	s_waitcnt vmcnt(27)
	v_add_u32_e32 v109, s24, v100
	ds_write_b128 v109, v[42:45]
	ds_write_b128 v109, v[46:49] offset:55296
	ds_write_b128 v109, v[50:53] offset:9216
	ds_write_b128 v109, v[54:57] offset:64512
	v_mov_b64_e32 v[18:19], v[10:11]
	v_mov_b64_e32 v[20:21], v[12:13]
	v_mov_b64_e32 v[22:23], v[14:15]
	v_mov_b64_e32 v[24:25], v[16:17]
	s_waitcnt lgkmcnt(0)
	s_barrier
	s_bfe_u32 s36, s23, 0x20000
	s_bfe_u32 s37, s23, 0x40002
	s_bfe_u32 s38, s23, 0x60006
	s_bfe_u32 s39, s23, 0x8000c
	s_lshl_b32 s40, s36, 1
	s_lshr_b32 s40, 0x1000, s40
	s_mul_i32 s39, s39, s40
	s_add_i32 s38, s38, -1
	s_lshl_b32 s38, s38, 7
	s_add_i32 s39, s39, s38
	s_lshl_b32 s39, s39, 7
	s_mul_i32 s37, s37, 0x208000
	s_add_i32 s39, s39, s37
	s_bitcmp1_b32 s23, 21
	s_cselect_b32 s39, s39, 0x80000000
	s_mul_i32 s36, s36, 0x2100000
	s_add_i32 s40, s36, 0x16a00000
	s_add_i32 s41, s36, 0x1cd00000
	s_add_i32 s42, s36, 0x10700000
	v_add_u32_e32 v105, s39, v101
	v_add_u32_e32 v106, s39, v102
	v_add_u32_e32 v107, s39, v103
	s_bitcmp1_b32 s22, 20
	s_cbranch_scc0 .Lp9n_nocompB
	s_and_b32 s99, s22, 63
	s_bfe_u32 s4, s22, 0x60006
	s_add_i32 s4, s4, -1
	s_lshl_b32 s4, s4, 6
	s_or_b32 s99, s99, s4
	s_add_i32 s4, s21, -1
	s_cmp_lt_i32 s4, 0
	s_cselect_b32 s4, 2, s4
	s_lshl_b32 s4, s4, 3
	s_lshr_b32 s5, s33, 4
	s_add_i32 s4, s4, s5
	s_lshl_b32 s4, s4, 11
	s_or_b32 s99, s99, s4
	s_bfe_u32 s4, s22, 0x8000c
	s_lshl_b32 s4, s4, 17
	s_or_b32 s99, s99, s4
	buffer_load_dwordx4 v[42:45], v105, s[16:19], s40 offen
	buffer_load_dwordx4 v[46:49], v105, s[16:19], s41 offen
	buffer_load_dwordx4 v[50:53], v106, s[16:19], s40 offen
	buffer_load_dwordx4 v[54:57], v106, s[16:19], s41 offen
	buffer_load_dwordx4 v[10:13], v107, s[16:19], s42 offen
	buffer_load_dwordx4 v[14:17], v107, s[16:19], s42 offen offset:64
	s_bitset1_b32 s99, 27
	s_branch .Lat_tile
.Lp9n_nocompB:
	buffer_load_dwordx4 v[42:45], v105, s[16:19], s40 offen
	buffer_load_dwordx4 v[46:49], v105, s[16:19], s41 offen
	buffer_load_dwordx4 v[50:53], v106, s[16:19], s40 offen
	buffer_load_dwordx4 v[54:57], v106, s[16:19], s41 offen
	buffer_load_dwordx4 v[10:13], v107, s[16:19], s42 offen
	buffer_load_dwordx4 v[14:17], v107, s[16:19], s42 offen offset:64
	buffer_store_dword v108, v108, s[16:19], 0 offen
	buffer_store_dword v108, v108, s[16:19], 0 offen
	buffer_store_dword v108, v108, s[16:19], 0 offen
	buffer_store_dword v108, v108, s[16:19], 0 offen
	buffer_store_dword v108, v108, s[16:19], 0 offen

.Lp9n_stepC:
	s_add_i32 s23, s20, 3
	v_readlane_b32 s22, v104, s20
	v_readlane_b32 s23, v104, s23
	s_mul_i32 s24, s21, 0x4800
	s_waitcnt vmcnt(27)
	v_add_u32_e32 v109, s24, v100
	ds_write_b128 v109, v[110:113]
	ds_write_b128 v109, v[114:117] offset:55296
	ds_write_b128 v109, v[118:121] offset:9216
	ds_write_b128 v109, v[122:125] offset:64512
	v_mov_b64_e32 v[18:19], v[126:127]
	v_mov_b64_e32 v[20:21], v[128:129]
	v_mov_b64_e32 v[22:23], v[130:131]
	v_mov_b64_e32 v[24:25], v[132:133]
	s_waitcnt lgkmcnt(0)
	s_barrier
	s_bfe_u32 s36, s23, 0x20000
	s_bfe_u32 s37, s23, 0x40002
	s_bfe_u32 s38, s23, 0x60006
	s_bfe_u32 s39, s23, 0x8000c
	s_lshl_b32 s40, s36, 1
	s_lshr_b32 s40, 0x1000, s40
	s_mul_i32 s39, s39, s40
	s_add_i32 s38, s38, -1
	s_lshl_b32 s38, s38, 7
	s_add_i32 s39, s39, s38
	s_lshl_b32 s39, s39, 7
	s_mul_i32 s37, s37, 0x208000
	s_add_i32 s39, s39, s37
	s_bitcmp1_b32 s23, 21
	s_cselect_b32 s39, s39, 0x80000000
	s_mul_i32 s36, s36, 0x2100000
	s_add_i32 s40, s36, 0x16a00000
	s_add_i32 s41, s36, 0x1cd00000
	s_add_i32 s42, s36, 0x10700000
	v_add_u32_e32 v105, s39, v101
	v_add_u32_e32 v106, s39, v102
	v_add_u32_e32 v107, s39, v103
	s_bitcmp1_b32 s22, 20
	s_cbranch_scc0 .Lp9n_nocompC
	s_and_b32 s99, s22, 63
	s_bfe_u32 s4, s22, 0x60006
	s_add_i32 s4, s4, -1
	s_lshl_b32 s4, s4, 6
	s_or_b32 s99, s99, s4
	s_add_i32 s4, s21, -1
	s_cmp_lt_i32 s4, 0
	s_cselect_b32 s4, 2, s4
	s_lshl_b32 s4, s4, 3
	s_lshr_b32 s5, s33, 4
	s_add_i32 s4, s4, s5
	s_lshl_b32 s4, s4, 11
	s_or_b32 s99, s99, s4
	s_bfe_u32 s4, s22, 0x8000c
	s_lshl_b32 s4, s4, 17
	s_or_b32 s99, s99, s4
	buffer_load_dwordx4 v[110:113], v105, s[16:19], s40 offen
	buffer_load_dwordx4 v[114:117], v105, s[16:19], s41 offen
	buffer_load_dwordx4 v[118:121], v106, s[16:19], s40 offen
	buffer_load_dwordx4 v[122:125], v106, s[16:19], s41 offen
	buffer_load_dwordx4 v[126:129], v107, s[16:19], s42 offen
	buffer_load_dwordx4 v[130:133], v107, s[16:19], s42 offen offset:64
	s_bitset1_b32 s99, 28
	s_branch .Lat_tile
.Lp9n_nocompC:
	buffer_load_dwordx4 v[110:113], v105, s[16:19], s40 offen
	buffer_load_dwordx4 v[114:117], v105, s[16:19], s41 offen
	buffer_load_dwordx4 v[118:121], v106, s[16:19], s40 offen
	buffer_load_dwordx4 v[122:125], v106, s[16:19], s41 offen
	buffer_load_dwordx4 v[126:129], v107, s[16:19], s42 offen
	buffer_load_dwordx4 v[130:133], v107, s[16:19], s42 offen offset:64
	buffer_store_dword v108, v108, s[16:19], 0 offen
	buffer_store_dword v108, v108, s[16:19], 0 offen
	buffer_store_dword v108, v108, s[16:19], 0 offen
	buffer_store_dword v108, v108, s[16:19], 0 offen
	buffer_store_dword v108, v108, s[16:19], 0 offen
